# baseline (speedup 1.0000x reference)
; __device__ __forceinline__ void gemm_phase(const int tid_, const GemmArgs& ga, u16* shm) {
;   const int nM = T / BM, nN = ga.nN, nwg = nM * nN;
;   int w = blockIdx.x;
;   if (w < nwg) {
;     const int lda = ga.lda, ldb = ga.ldb, nt = ga.K / BK;
.LBB0_231:
	s_nop 0
	s_nop 0
	s_nop 0
	s_nop 0
	s_nop 0
	s_nop 0
	s_nop 0
	s_nop 0
	s_nop 0
	s_nop 0
	s_nop 0
	s_nop 0
	s_nop 0
	s_nop 0
	s_nop 0
	s_nop 0
	s_nop 0
	s_nop 0
	s_nop 0
	s_nop 0
	s_nop 0
	s_nop 0
	s_nop 0
	s_nop 0
	s_nop 0
	s_nop 0
	s_nop 0
	s_nop 0
	s_mov_b64 s[4:5], 0

; #define STAGE_A(Poff, off, hrow) do { const unsigned _s = (off) + (unsigned)(hrow) * lda2;                                \
;     GLDS(ldsw + (Poff), offA, srdA, _s); GLDS(ldsw + (Poff) + 8192, offA, srdA, _s + lda128); } while (0)
; #define STAGE_B(Poff, off, hrow) do { const unsigned _s = (off) + (unsigned)(hrow) * ldb2;                                \
;     GLDS(ldsw + (Poff), offB, srdB, _s); GLDS(ldsw + (Poff) + 8192, offB, srdB, _s + ldb128); } while (0)
; #define WAIT_V(n) asm volatile("s_waitcnt vmcnt(" #n ")" ::: "memory")
; #define BAR __builtin_amdgcn_s_barrier()
; __device__ __forceinline__ void gemm_phase(const int tid_, const GemmArgs& ga, u16* shm) {
;     ...
;     const int lda = ga.lda, ldb = ga.ldb, nt = ga.K / BK;
;     const int wid = tid_ >> 6, lane = tid_ & 63, wr = wid >> 2, wc = wid & 3, fr = lane & 15, fq = lane >> 4;
;     int sr_, sc_; stage_rc(tid_ * 16, sr_, sc_);
;     const unsigned offA = (unsigned)(sr_ * lda + sc_) * 2u, offB = (unsigned)(sr_ * ldb + sc_) * 2u;
;     const int obs = lds_byte(fr, fq * 8);
;     const int aoff = wr * 8192 + obs, boff = wc * 4096 + obs;
;     f32x4 acc[2][2][4][2] = {};
;     bf16x8 At[4][2], B0[2][2], B1[2][2];
;     int brow, bcol; tile_coords(w, nM, nN, brow, bcol);
;     const unsigned lda2 = (unsigned)lda * 2u, ldb2 = (unsigned)ldb * 2u, lda128 = (unsigned)lda * 128u, ldb128 = (unsigned)ldb * 128u;
;     const __amdgpu_buffer_rsrc_t srdA = __builtin_amdgcn_make_buffer_rsrc((void*)ga.A, (short)0, 0x7fffffff, 0x00020000);
;     const __amdgpu_buffer_rsrc_t srdB = __builtin_amdgcn_make_buffer_rsrc((void*)ga.Bt, (short)0, 0x7fffffff, 0x00020000);
;     const unsigned ldsw = (unsigned)(uintptr_t)shm + (unsigned)__builtin_amdgcn_readfirstlane(wid) * 1024u;
;     unsigned gA = ((unsigned)brow * (unsigned)lda + (ga.agrp ? (unsigned)((bcol >> 9) << 9) : 0u)) * 2u;
;     unsigned gB = (unsigned)bcol * ldb2;
;     STAGE_B(SBO(0, 0), gB, 0); STAGE_A(SAO(0, 0), gA, 0);
;     STAGE_B(SBO(0, 1), gB, HALF); STAGE_A(SAO(0, 1), gA, HALF);
;     if (wr == 1) BAR;
;     WAIT_V(4); BAR;
;     STAGE_B(SBO(1, 0), gB + 128, 0); STAGE_A(SAO(1, 0), gA + 128, 0); STAGE_B(SBO(1, 1), gB + 128, HALF);
;     WAIT_V(6); BAR;
.LBB0_310:
	s_or_b64 exec, exec, s[4:5]
	v_readfirstlane_b32 s4, v151
	s_cmp_eq_u32 s4, 0
	s_cbranch_scc0 .Lg_noprio
	s_setprio 1
.Lg_noprio:
	v_and_b32_e32 v1, 15, v186
	v_lshlrev_b32_e32 v4, 2, v186
	v_and_b32_e32 v2, 48, v186
	v_lshlrev_b32_e32 v1, 6, v1
	v_and_b32_e32 v4, 32, v4
	v_or_b32_e32 v3, v1, v2
	v_bitop3_b32 v1, v1, v4, v2 bitop3:0x36
	v_lshlrev_b32_e32 v0, 12, v0
	s_movk_i32 s4, 0x3000
	v_and_or_b32 v0, v0, s4, v1
	v_readlane_b32 s4, v250, 52
	s_lshr_b32 s67, s60, 6
	s_lshl_b32 s4, s4, 8
	s_or_b32 s5, s1, 0x80
	s_cmp_lg_u32 0, -1
	s_cselect_b32 s7, 0, 0
	s_add_i32 s6, s7, s6
	s_waitcnt vmcnt(0)
	s_barrier
	s_add_i32 s98, s6, 0x18000
	s_mov_b32 s46, s38
	s_mov_b32 s47, s39
	s_mov_b32 m0, s98
	s_nop 0
	buffer_load_dwordx4 v223, s[44:47], s5 offen lds
	s_add_i32 s99, s6, 0x1a000
	s_add_i32 s5, s5, s63
	s_mov_b32 m0, s99
	s_nop 0
	buffer_load_dwordx4 v223, s[44:47], s5 offen lds
	s_or_b32 s7, s54, 0x80
	s_add_i32 s68, s6, 0x8000
	s_mov_b32 s50, s38
	s_mov_b32 s51, s39
	s_mov_b32 m0, s68
	s_nop 0
	buffer_load_dwordx4 v222, s[48:51], s7 offen lds
	s_add_i32 s69, s6, 0xa000
	s_add_i32 s7, s7, s62
	s_mov_b32 m0, s69
	s_nop 0
	buffer_load_dwordx4 v222, s[48:51], s7 offen lds
	s_add_i32 s5, s5, s63
	s_add_i32 s42, s6, 0x1c000
	s_mov_b32 m0, s42
	s_nop 0
	buffer_load_dwordx4 v223, s[44:47], s5 offen lds
	v_lshlrev_b32_e32 v2, 13, v151
	s_add_i32 s43, s6, 0x1e000
	s_add_i32 s5, s5, s63
	s_mov_b32 m0, s43
	s_nop 0
	buffer_load_dwordx4 v223, s[44:47], s5 offen lds
	v_bitop3_b32 v2, v3, v2, v4 bitop3:0xde
	s_waitcnt vmcnt(6)
	v_mov_b32_e32 v96, v97
	v_mov_b32_e32 v98, v97
	v_mov_b32_e32 v99, v97
	v_add_u32_e32 v224, 0, v0
	v_add_u32_e32 v225, 0, v2
	v_mov_b64_e32 v[0:1], v[96:97]
	v_mov_b64_e32 v[4:5], v[96:97]
	v_mov_b64_e32 v[8:9], v[96:97]
	v_mov_b64_e32 v[12:13], v[96:97]
	v_mov_b64_e32 v[16:17], v[96:97]
	v_mov_b64_e32 v[20:21], v[96:97]
	v_mov_b64_e32 v[24:25], v[96:97]
	v_mov_b64_e32 v[28:29], v[96:97]
	v_mov_b64_e32 v[32:33], v[96:97]
	v_mov_b64_e32 v[36:37], v[96:97]
	v_mov_b64_e32 v[40:41], v[96:97]
	v_mov_b64_e32 v[44:45], v[96:97]
	v_mov_b64_e32 v[48:49], v[96:97]
	v_mov_b64_e32 v[52:53], v[96:97]
	v_mov_b64_e32 v[56:57], v[96:97]
	v_mov_b64_e32 v[60:61], v[96:97]
	v_mov_b64_e32 v[64:65], v[96:97]
	v_mov_b64_e32 v[68:69], v[96:97]
	v_mov_b64_e32 v[72:73], v[96:97]
	v_mov_b64_e32 v[76:77], v[96:97]
	v_mov_b64_e32 v[80:81], v[96:97]
	v_mov_b64_e32 v[84:85], v[96:97]
	v_mov_b64_e32 v[88:89], v[96:97]
	v_mov_b64_e32 v[92:93], v[96:97]
	v_mov_b64_e32 v[102:103], v[98:99]
	v_mov_b64_e32 v[106:107], v[98:99]
	v_mov_b64_e32 v[110:111], v[98:99]
	v_mov_b64_e32 v[114:115], v[98:99]
	v_mov_b64_e32 v[118:119], v[98:99]
	v_mov_b64_e32 v[122:123], v[98:99]
	v_mov_b64_e32 v[126:127], v[98:99]
	v_mov_b64_e32 v[130:131], v[98:99]
	s_bitset1_b32 s4, 7
	s_add_i32 s66, s6, 0xc000
	s_add_i32 s18, s6, 0xe000
	v_mov_b64_e32 v[2:3], v[98:99]
	v_mov_b64_e32 v[6:7], v[98:99]
	v_mov_b64_e32 v[10:11], v[98:99]
	v_mov_b64_e32 v[14:15], v[98:99]
	v_mov_b64_e32 v[18:19], v[98:99]
	v_mov_b64_e32 v[22:23], v[98:99]
	v_mov_b64_e32 v[26:27], v[98:99]
	v_mov_b64_e32 v[30:31], v[98:99]
	v_mov_b64_e32 v[34:35], v[98:99]
	v_mov_b64_e32 v[38:39], v[98:99]
	v_mov_b64_e32 v[42:43], v[98:99]
	v_mov_b64_e32 v[46:47], v[98:99]
	v_mov_b64_e32 v[50:51], v[98:99]
	v_mov_b64_e32 v[54:55], v[98:99]
	s_mov_b32 s6, s3
	v_mov_b64_e32 v[58:59], v[98:99]
	v_mov_b64_e32 v[62:63], v[98:99]
	v_mov_b64_e32 v[66:67], v[98:99]
	v_mov_b64_e32 v[70:71], v[98:99]
	v_mov_b64_e32 v[74:75], v[98:99]
	v_mov_b64_e32 v[78:79], v[98:99]
	v_mov_b64_e32 v[82:83], v[98:99]
	v_mov_b64_e32 v[86:87], v[98:99]
	v_mov_b64_e32 v[90:91], v[98:99]
	v_mov_b64_e32 v[94:95], v[98:99]
	v_mov_b64_e32 v[100:101], v[96:97]
	v_mov_b64_e32 v[104:105], v[96:97]
	v_mov_b64_e32 v[108:109], v[96:97]
	v_mov_b64_e32 v[112:113], v[96:97]
	v_mov_b64_e32 v[116:117], v[96:97]
	v_mov_b64_e32 v[120:121], v[96:97]
	v_mov_b64_e32 v[124:125], v[96:97]
	v_mov_b64_e32 v[128:129], v[96:97]
	s_barrier
	v_writelane_b32 v250, s4, 58
	s_branch .LBB0_312

; #define WAIT_V(n) asm volatile("s_waitcnt vmcnt(" #n ")" ::: "memory")
; #define BAR __builtin_amdgcn_s_barrier()
; __device__ __forceinline__ void gemm_phase(const int tid_, const GemmArgs& ga, u16* shm) {
;     ...
;     WAIT_V(0);
;     if (wr == 0) BAR;
;     __syncthreads();
.LBB0_564:
	s_setprio 0
	s_waitcnt vmcnt(0)
	s_movk_i32 s0, 0x100
	v_cmp_gt_u32_e32 vcc, s0, v150
	s_and_saveexec_b64 s[4:5], vcc
	s_cbranch_execz .LBB0_566
	s_barrier
